# attention block epilogue: 16 dwordx2 stores paired into 8 dwordx4 stores via v_permlane32_swap
# baseline (speedup 1.0000x reference)
.LBB0_225:
	s_add_i32 s82, s82, s76
	v_or_b32_e32 v0, s82, v183
	v_lshlrev_b32_e32 v2, 3, v0
	v_and_b32_e32 v14, 0xffffff80, v2
	v_or_b32_e32 v112, s78, v14
	v_ashrrev_i32_e32 v113, 31, v112
	v_lshlrev_b64 v[112:113], 10, v[112:113]
	v_lshl_add_u64 v[112:113], v[172:173], 0, v[112:113]
	global_load_dwordx2 v[114:115], v[112:113], off
	global_load_dwordx2 v[116:117], v[112:113], off offset:16
	global_load_dwordx2 v[118:119], v[112:113], off offset:32
	global_load_dwordx2 v[120:121], v[112:113], off offset:48
	v_or_b32_e32 v110, s79, v14
	v_ashrrev_i32_e32 v111, 31, v110
	v_lshlrev_b64 v[110:111], 10, v[110:111]
	v_lshl_add_u64 v[110:111], v[172:173], 0, v[110:111]
	global_load_dwordx2 v[122:123], v[110:111], off
	global_load_dwordx2 v[124:125], v[110:111], off offset:16
	global_load_dwordx2 v[126:127], v[110:111], off offset:32
	global_load_dwordx2 v[128:129], v[110:111], off offset:48
	v_or_b32_e32 v112, v14, v210
	v_ashrrev_i32_e32 v113, 31, v112
	v_lshlrev_b64 v[112:113], 10, v[112:113]
	v_lshl_add_u64 v[112:113], v[172:173], 0, v[112:113]
	global_load_dwordx2 v[130:131], v[112:113], off
	v_or_b32_e32 v110, v14, v212
	v_ashrrev_i32_e32 v111, 31, v110
	v_lshlrev_b64 v[110:111], 10, v[110:111]
	v_lshl_add_u64 v[110:111], v[172:173], 0, v[110:111]
	global_load_dwordx2 v[132:133], v[110:111], off offset:16
	v_or_b32_e32 v112, v14, v214
	v_ashrrev_i32_e32 v113, 31, v112
	v_lshlrev_b64 v[112:113], 10, v[112:113]
	v_lshl_add_u64 v[112:113], v[172:173], 0, v[112:113]
	global_load_dwordx2 v[134:135], v[112:113], off offset:32
	v_or_b32_e32 v110, v14, v216
	v_ashrrev_i32_e32 v111, 31, v110
	v_lshlrev_b64 v[110:111], 10, v[110:111]
	v_lshl_add_u64 v[110:111], v[172:173], 0, v[110:111]
	global_load_dwordx2 v[136:137], v[110:111], off offset:48
	v_or_b32_e32 v112, v14, v209
	v_ashrrev_i32_e32 v113, 31, v112
	v_lshlrev_b64 v[112:113], 10, v[112:113]
	v_lshl_add_u64 v[112:113], v[172:173], 0, v[112:113]
	global_load_dwordx2 v[138:139], v[112:113], off
	v_or_b32_e32 v110, v14, v219
	v_ashrrev_i32_e32 v111, 31, v110
	v_lshlrev_b64 v[110:111], 10, v[110:111]
	v_lshl_add_u64 v[110:111], v[172:173], 0, v[110:111]
	global_load_dwordx2 v[140:141], v[110:111], off offset:16
	v_or_b32_e32 v112, v14, v221
	v_ashrrev_i32_e32 v113, 31, v112
	v_lshlrev_b64 v[112:113], 10, v[112:113]
	v_lshl_add_u64 v[112:113], v[172:173], 0, v[112:113]
	global_load_dwordx2 v[142:143], v[112:113], off offset:32
	v_or_b32_e32 v110, v14, v223
	v_ashrrev_i32_e32 v111, 31, v110
	v_lshlrev_b64 v[110:111], 10, v[110:111]
	v_lshl_add_u64 v[110:111], v[172:173], 0, v[110:111]
	global_load_dwordx2 v[144:145], v[110:111], off offset:48
	v_lshlrev_b32_e32 v2, 5, v0
	v_and_b32_e32 v8, 0x1e0, v2
	v_lshlrev_b32_e32 v2, 1, v0
	v_and_b32_e32 v9, 16, v2
	v_or_b32_e32 v2, s78, v14
	v_ashrrev_i32_e32 v3, 31, v2
	v_lshlrev_b64 v[2:3], 10, v[2:3]
	v_lshl_add_u64 v[4:5], v[172:173], 0, v[2:3]
	v_lshlrev_b32_e32 v0, 6, v0
	s_ashr_i32 s2, s82, 2
	v_and_b32_e32 v0, 0x1c00, v0
	v_readlane_b32 s0, v250, 38
	s_andn2_b32 s2, s2, 63
	v_or3_b32 v10, v9, v8, v189
	v_or_b32_e32 v15, s0, v0
	s_or_b32 s0, s2, s80
	s_ashr_i32 s1, s0, 31
	s_lshl_b64 s[0:1], s[0:1], 15
	s_add_u32 s0, s50, s0
	s_addc_u32 s1, s51, s1
	v_mov_b32_e32 v13, v1
	v_mov_b32_e32 v11, v1
	s_add_i32 s81, s81, 1
	s_cmp_eq_u32 s81, 4
	v_cndmask_b32_e64 v109, 8, 0, s[42:43]
	v_mov_b32_e32 v105, 0
	v_cndmask_b32_e64 v104, 8, 0, s[42:43]
	s_waitcnt vmcnt(15)
	v_lshlrev_b32_e32 v0, 16, v114
	v_and_b32_e32 v2, 0xffff0000, v114
	v_mul_f32_e32 v0, v80, v0
	v_mul_f32_e32 v2, v81, v2
	v_cvt_pk_bf16_f32 v110, v0, v2
	v_lshlrev_b32_e32 v0, 16, v115
	v_and_b32_e32 v3, 0xffff0000, v115
	v_mul_f32_e32 v0, v82, v0
	v_mul_f32_e32 v3, v83, v3
	v_cvt_pk_bf16_f32 v111, v0, v3
	v_or_b32_e32 v0, v10, v15
	v_lshlrev_b32_e32 v0, 1, v0
	v_add_u32_e32 v108, v109, v0
	v_bitop3_b32 v80, v8, v9, v198 bitop3:0x36
	v_bitop3_b32 v81, v8, v9, v199 bitop3:0x36
	v_mov_b32_e32 v9, v1
	s_waitcnt vmcnt(14)
	v_lshlrev_b32_e32 v6, 16, v116
	v_and_b32_e32 v2, 0xffff0000, v116
	v_mul_f32_e32 v6, v84, v6
	v_mul_f32_e32 v2, v85, v2
	v_cvt_pk_bf16_f32 v112, v6, v2
	v_lshlrev_b32_e32 v2, 16, v117
	v_mul_f32_e32 v2, v86, v2
	v_and_b32_e32 v3, 0xffff0000, v117
	v_mul_f32_e32 v3, v87, v3
	v_cvt_pk_bf16_f32 v113, v2, v3
	v_add_lshl_u32 v2, v10, v15, 1
	s_nop 1
	v_permlane32_swap_b32_e32 v110, v112
	v_permlane32_swap_b32_e32 v111, v113
	global_store_dwordx4 v108, v[110:113], s[0:1]
	s_waitcnt vmcnt(14)
	v_lshlrev_b32_e32 v3, 16, v118
	v_and_b32_e32 v6, 0xffff0000, v118
	v_mul_f32_e32 v3, v88, v3
	v_mul_f32_e32 v6, v89, v6
	v_cvt_pk_bf16_f32 v110, v3, v6
	v_lshlrev_b32_e32 v3, 16, v119
	v_and_b32_e32 v7, 0xffff0000, v119
	v_mul_f32_e32 v3, v90, v3
	v_mul_f32_e32 v7, v91, v7
	v_cvt_pk_bf16_f32 v111, v3, v7
	v_or_b32_e32 v3, v80, v15
	v_lshlrev_b32_e32 v12, 1, v3
	v_add_u32_e32 v108, v109, v12
	s_waitcnt vmcnt(13)
	v_lshlrev_b32_e32 v3, 16, v120
	v_and_b32_e32 v4, 0xffff0000, v120
	v_mul_f32_e32 v3, v92, v3
	v_mul_f32_e32 v4, v93, v4
	v_cvt_pk_bf16_f32 v112, v3, v4
	v_lshlrev_b32_e32 v3, 16, v121
	v_and_b32_e32 v5, 0xffff0000, v121
	v_mul_f32_e32 v3, v94, v3
	v_mul_f32_e32 v5, v95, v5
	v_cvt_pk_bf16_f32 v113, v3, v5
	v_or_b32_e32 v3, v81, v15
	v_lshlrev_b32_e32 v10, 1, v3
	s_nop 1
	v_permlane32_swap_b32_e32 v110, v112
	v_permlane32_swap_b32_e32 v111, v113
	global_store_dwordx4 v108, v[110:113], s[0:1]
	v_or_b32_e32 v4, s79, v14
	v_ashrrev_i32_e32 v5, 31, v4
	v_lshlrev_b64 v[4:5], 10, v[4:5]
	v_lshl_add_u64 v[4:5], v[172:173], 0, v[4:5]
	s_waitcnt vmcnt(13)
	v_lshlrev_b32_e32 v3, 16, v122
	v_and_b32_e32 v6, 0xffff0000, v122
	v_mul_f32_e32 v3, v64, v3
	v_mul_f32_e32 v6, v65, v6
	v_cvt_pk_bf16_f32 v110, v3, v6
	v_lshlrev_b32_e32 v3, 16, v123
	v_and_b32_e32 v7, 0xffff0000, v123
	v_mul_f32_e32 v7, v67, v7
	v_mul_f32_e32 v3, v66, v3
	v_cvt_pk_bf16_f32 v111, v3, v7
	v_add_u32_e32 v108, v109, v2
	v_mov_b32_e32 v3, v1
	s_waitcnt vmcnt(12)
	v_lshlrev_b32_e32 v8, 16, v124
	v_and_b32_e32 v6, 0xffff0000, v124
	v_mul_f32_e32 v8, v68, v8
	v_mul_f32_e32 v6, v69, v6
	v_cvt_pk_bf16_f32 v112, v8, v6
	v_lshlrev_b32_e32 v8, 16, v125
	v_and_b32_e32 v7, 0xffff0000, v125
	v_mul_f32_e32 v8, v70, v8
	v_mul_f32_e32 v7, v71, v7
	v_cvt_pk_bf16_f32 v113, v8, v7
	v_add_u32_e32 v8, 0x400, v2
	s_nop 1
	v_permlane32_swap_b32_e32 v110, v112
	v_permlane32_swap_b32_e32 v111, v113
	global_store_dwordx4 v108, v[110:113], s[0:1] offset:1024
	s_waitcnt vmcnt(12)
	v_lshlrev_b32_e32 v64, 16, v126
	v_and_b32_e32 v6, 0xffff0000, v126
	v_mul_f32_e32 v64, v72, v64
	v_mul_f32_e32 v6, v73, v6
	v_cvt_pk_bf16_f32 v110, v64, v6
	v_lshlrev_b32_e32 v6, 16, v127
	v_mul_f32_e32 v6, v74, v6
	v_and_b32_e32 v7, 0xffff0000, v127
	v_mul_f32_e32 v7, v75, v7
	v_cvt_pk_bf16_f32 v111, v6, v7
	v_add_lshl_u32 v6, v80, v15, 1
	v_add_u32_e32 v108, v109, v6
	v_mov_b32_e32 v7, v1
	s_waitcnt vmcnt(11)
	v_lshlrev_b32_e32 v64, 16, v128
	v_and_b32_e32 v4, 0xffff0000, v128
	v_mul_f32_e32 v64, v76, v64
	v_mul_f32_e32 v4, v77, v4
	v_cvt_pk_bf16_f32 v112, v64, v4
	v_lshlrev_b32_e32 v4, 16, v129
	v_mul_f32_e32 v4, v78, v4
	v_and_b32_e32 v5, 0xffff0000, v129
	v_mul_f32_e32 v5, v79, v5
	v_cvt_pk_bf16_f32 v113, v4, v5
	v_add_lshl_u32 v4, v81, v15, 1
	s_nop 1
	v_permlane32_swap_b32_e32 v110, v112
	v_permlane32_swap_b32_e32 v111, v113
	global_store_dwordx4 v108, v[110:113], s[0:1] offset:1024
	v_or_b32_e32 v64, v14, v210
	v_ashrrev_i32_e32 v65, 31, v64
	v_lshlrev_b64 v[64:65], 10, v[64:65]
	v_lshl_add_u64 v[64:65], v[172:173], 0, v[64:65]
	v_mov_b32_e32 v5, v1
	s_waitcnt vmcnt(11)
	v_lshlrev_b32_e32 v15, 16, v130
	v_mul_f32_e32 v15, v48, v15
	v_and_b32_e32 v48, 0xffff0000, v130
	v_mul_f32_e32 v48, v49, v48
	v_cvt_pk_bf16_f32 v110, v15, v48
	v_lshlrev_b32_e32 v15, 16, v131
	v_mul_f32_e32 v15, v50, v15
	v_and_b32_e32 v49, 0xffff0000, v131
	v_or_b32_e32 v50, s2, v211
	v_mul_f32_e32 v49, v51, v49
	v_ashrrev_i32_e32 v51, 31, v50
	v_lshlrev_b64 v[50:51], 15, v[50:51]
	v_lshl_add_u64 v[50:51], s[50:51], 0, v[50:51]
	v_lshl_add_u64 v[50:51], v[50:51], 0, v[0:1]
	v_cvt_pk_bf16_f32 v111, v15, v49
	v_lshl_add_u64 v[106:107], v[50:51], 0, v[104:105]
	v_or_b32_e32 v48, v14, v212
	v_ashrrev_i32_e32 v49, 31, v48
	v_lshlrev_b64 v[48:49], 10, v[48:49]
	v_lshl_add_u64 v[48:49], v[172:173], 0, v[48:49]
	v_or_b32_e32 v50, s2, v213
	v_ashrrev_i32_e32 v51, 31, v50
	v_lshlrev_b64 v[50:51], 15, v[50:51]
	v_lshl_add_u64 v[50:51], s[50:51], 0, v[50:51]
	v_lshl_add_u64 v[50:51], v[50:51], 0, v[2:3]
	s_waitcnt vmcnt(10)
	v_lshlrev_b32_e32 v0, 16, v132
	v_and_b32_e32 v15, 0xffff0000, v132
	v_mul_f32_e32 v0, v52, v0
	v_mul_f32_e32 v15, v53, v15
	v_cvt_pk_bf16_f32 v112, v0, v15
	v_lshlrev_b32_e32 v0, 16, v133
	v_and_b32_e32 v15, 0xffff0000, v133
	v_mul_f32_e32 v0, v54, v0
	v_mul_f32_e32 v15, v55, v15
	v_cvt_pk_bf16_f32 v113, v0, v15
	s_nop 1
	v_permlane32_swap_b32_e32 v110, v112
	v_permlane32_swap_b32_e32 v111, v113
	global_store_dwordx4 v[106:107], v[110:113], off
	v_or_b32_e32 v48, v14, v214
	v_ashrrev_i32_e32 v49, 31, v48
	v_lshlrev_b64 v[48:49], 10, v[48:49]
	v_lshl_add_u64 v[48:49], v[172:173], 0, v[48:49]
	v_or_b32_e32 v50, s2, v215
	v_ashrrev_i32_e32 v51, 31, v50
	v_lshlrev_b64 v[50:51], 15, v[50:51]
	v_lshl_add_u64 v[50:51], s[50:51], 0, v[50:51]
	v_lshl_add_u64 v[12:13], v[50:51], 0, v[12:13]
	s_waitcnt vmcnt(10)
	v_lshlrev_b32_e32 v0, 16, v134
	v_and_b32_e32 v15, 0xffff0000, v134
	v_mul_f32_e32 v0, v56, v0
	v_mul_f32_e32 v15, v57, v15
	v_cvt_pk_bf16_f32 v110, v0, v15
	v_lshlrev_b32_e32 v0, 16, v135
	v_and_b32_e32 v15, 0xffff0000, v135
	v_mul_f32_e32 v0, v58, v0
	v_mul_f32_e32 v15, v59, v15
	v_cvt_pk_bf16_f32 v111, v0, v15
	v_lshl_add_u64 v[106:107], v[12:13], 0, v[104:105]
	v_or_b32_e32 v12, v14, v216
	v_ashrrev_i32_e32 v13, 31, v12
	v_lshlrev_b64 v[12:13], 10, v[12:13]
	v_lshl_add_u64 v[12:13], v[172:173], 0, v[12:13]
	v_or_b32_e32 v48, s2, v217
	v_ashrrev_i32_e32 v49, 31, v48
	v_lshlrev_b64 v[48:49], 15, v[48:49]
	v_lshl_add_u64 v[48:49], s[50:51], 0, v[48:49]
	v_lshl_add_u64 v[10:11], v[48:49], 0, v[10:11]
	s_waitcnt vmcnt(9)
	v_lshlrev_b32_e32 v0, 16, v136
	v_and_b32_e32 v12, 0xffff0000, v136
	v_mul_f32_e32 v0, v60, v0
	v_mul_f32_e32 v12, v61, v12
	v_cvt_pk_bf16_f32 v112, v0, v12
	v_lshlrev_b32_e32 v0, 16, v137
	v_and_b32_e32 v13, 0xffff0000, v137
	v_mul_f32_e32 v13, v63, v13
	v_mul_f32_e32 v0, v62, v0
	v_cvt_pk_bf16_f32 v113, v0, v13
	s_nop 1
	v_permlane32_swap_b32_e32 v110, v112
	v_permlane32_swap_b32_e32 v111, v113
	global_store_dwordx4 v[106:107], v[110:113], off
	v_or_b32_e32 v10, v14, v209
	v_ashrrev_i32_e32 v11, 31, v10
	v_lshlrev_b64 v[10:11], 10, v[10:11]
	v_lshl_add_u64 v[10:11], v[172:173], 0, v[10:11]
	v_or_b32_e32 v12, s2, v218
	v_ashrrev_i32_e32 v13, 31, v12
	v_lshlrev_b64 v[12:13], 15, v[12:13]
	v_lshl_add_u64 v[12:13], s[50:51], 0, v[12:13]
	v_lshl_add_u64 v[2:3], v[12:13], 0, v[2:3]
	s_waitcnt vmcnt(9)
	v_lshlrev_b32_e32 v0, 16, v138
	v_and_b32_e32 v10, 0xffff0000, v138
	v_mul_f32_e32 v0, v32, v0
	v_mul_f32_e32 v10, v33, v10
	v_cvt_pk_bf16_f32 v110, v0, v10
	v_lshlrev_b32_e32 v0, 16, v139
	v_and_b32_e32 v11, 0xffff0000, v139
	v_mul_f32_e32 v11, v35, v11
	v_mul_f32_e32 v0, v34, v0
	v_cvt_pk_bf16_f32 v111, v0, v11
	v_lshl_add_u64 v[106:107], v[2:3], 0, v[104:105]
	v_or_b32_e32 v2, v14, v219
	v_ashrrev_i32_e32 v3, 31, v2
	v_lshlrev_b64 v[2:3], 10, v[2:3]
	v_lshl_add_u64 v[2:3], v[172:173], 0, v[2:3]
	v_or_b32_e32 v10, s2, v220
	v_ashrrev_i32_e32 v11, 31, v10
	v_lshlrev_b64 v[10:11], 15, v[10:11]
	v_lshl_add_u64 v[10:11], s[50:51], 0, v[10:11]
	v_lshl_add_u64 v[8:9], v[10:11], 0, v[8:9]
	s_waitcnt vmcnt(8)
	v_lshlrev_b32_e32 v0, 16, v140
	v_and_b32_e32 v2, 0xffff0000, v140
	v_mul_f32_e32 v0, v36, v0
	v_mul_f32_e32 v2, v37, v2
	v_cvt_pk_bf16_f32 v112, v0, v2
	v_lshlrev_b32_e32 v0, 16, v141
	v_and_b32_e32 v3, 0xffff0000, v141
	v_mul_f32_e32 v3, v39, v3
	v_mul_f32_e32 v0, v38, v0
	v_cvt_pk_bf16_f32 v113, v0, v3
	s_nop 1
	v_permlane32_swap_b32_e32 v110, v112
	v_permlane32_swap_b32_e32 v111, v113
	global_store_dwordx4 v[106:107], v[110:113], off offset:1024
	v_or_b32_e32 v2, v14, v221
	v_ashrrev_i32_e32 v3, 31, v2
	v_lshlrev_b64 v[2:3], 10, v[2:3]
	v_lshl_add_u64 v[2:3], v[172:173], 0, v[2:3]
	v_or_b32_e32 v8, s2, v222
	v_ashrrev_i32_e32 v9, 31, v8
	v_lshlrev_b64 v[8:9], 15, v[8:9]
	v_lshl_add_u64 v[8:9], s[50:51], 0, v[8:9]
	v_lshl_add_u64 v[6:7], v[8:9], 0, v[6:7]
	s_waitcnt vmcnt(8)
	v_lshlrev_b32_e32 v0, 16, v142
	v_and_b32_e32 v2, 0xffff0000, v142
	v_mul_f32_e32 v0, v40, v0
	v_mul_f32_e32 v2, v41, v2
	v_cvt_pk_bf16_f32 v110, v0, v2
	v_lshlrev_b32_e32 v0, 16, v143
	v_and_b32_e32 v3, 0xffff0000, v143
	v_mul_f32_e32 v3, v43, v3
	v_mul_f32_e32 v0, v42, v0
	v_cvt_pk_bf16_f32 v111, v0, v3
	v_lshl_add_u64 v[106:107], v[6:7], 0, v[104:105]
	v_or_b32_e32 v2, v14, v223
	v_ashrrev_i32_e32 v3, 31, v2
	v_lshlrev_b64 v[2:3], 10, v[2:3]
	v_lshl_add_u64 v[2:3], v[172:173], 0, v[2:3]
	v_or_b32_e32 v6, s2, v224
	v_ashrrev_i32_e32 v7, 31, v6
	v_lshlrev_b64 v[6:7], 15, v[6:7]
	v_lshl_add_u64 v[6:7], s[50:51], 0, v[6:7]
	v_lshl_add_u64 v[4:5], v[6:7], 0, v[4:5]
	s_waitcnt vmcnt(7)
	v_lshlrev_b32_e32 v0, 16, v144
	v_and_b32_e32 v2, 0xffff0000, v144
	v_mul_f32_e32 v0, v44, v0
	v_mul_f32_e32 v2, v45, v2
	v_cvt_pk_bf16_f32 v112, v0, v2
	v_lshlrev_b32_e32 v0, 16, v145
	v_and_b32_e32 v3, 0xffff0000, v145
	v_mul_f32_e32 v3, v47, v3
	v_mul_f32_e32 v0, v46, v0
	v_cvt_pk_bf16_f32 v113, v0, v3
	s_nop 1
	v_permlane32_swap_b32_e32 v110, v112
	v_permlane32_swap_b32_e32 v111, v113
	global_store_dwordx4 v[106:107], v[110:113], off offset:1024
	s_cbranch_scc1 .LBB0_223
